# 64-byte alignment of the five hot K-loop head labels
# baseline (speedup 1.0000x reference)
.LBB0_383:
	s_ashr_i32 s67, s66, 31
	s_lshl_b64 s[26:27], s[66:67], 19
	s_add_u32 s26, s40, s26
	s_addc_u32 s27, s41, s27
	s_and_b64 s[34:35], s[8:9], exec
	s_cselect_b32 s34, s27, s5
	s_cselect_b32 s35, s26, s4
	s_ashr_i32 s29, s28, 31
	s_lshl_b64 s[38:39], s[28:29], 19
	s_add_u32 s62, s10, s38
	s_addc_u32 s63, s11, s39
	s_and_b64 s[38:39], s[8:9], exec
	s_cselect_b32 s29, s63, s83
	s_cselect_b32 s38, s62, s82
	s_add_u32 s39, s82, 0x100
	s_addc_u32 s67, s83, 0
	s_mov_b32 s94, -2
	s_mov_b64 vcc, 0
	v_lshl_add_u64 v[132:133], s[4:5], 0, v[168:169]
	ds_read_b128 v[134:137], v199
	ds_read_b128 v[138:141], v200
	ds_read_b128 v[142:145], v201
	ds_read_b128 v[146:149], v202
	ds_read_b128 v[150:153], v203
	ds_read_b128 v[174:177], v204
	ds_read_b128 v[178:181], v205
	ds_read_b128 v[182:185], v206
	s_add_u32 s24, s4, vcc_lo
	s_addc_u32 s25, s5, vcc_hi
	s_add_u32 s24, s24, 0x100
	s_addc_u32 s25, s25, 0
	s_add_u32 s82, s39, vcc_lo
	s_addc_u32 s83, s67, vcc_hi
	s_cmpk_eq_i32 vcc_lo, 0x700
	s_cselect_b32 s87, s29, s83
	s_cselect_b32 s86, s38, s82
	s_cselect_b32 s83, s34, s25
	s_cselect_b32 s82, s35, s24
	v_lshl_add_u64 v[154:155], v[132:133], 0, vcc
	v_lshl_add_u64 v[250:251], v[154:155], 0, s[48:49]
	s_add_i32 m0, s79, 0x8000
	s_mov_b64 s[24:25], 0x20080
	ds_read_b128 v[218:221], v207
	ds_read_b128 v[222:225], v207 offset:2048
	ds_read_b128 v[226:229], v208
	ds_read_b128 v[230:233], v208 offset:2048
	ds_read_b128 v[234:237], v207 offset:4096
	ds_read_b128 v[238:241], v207 offset:6144
	ds_read_b128 v[242:245], v208 offset:4096
	ds_read_b128 v[246:249], v208 offset:6144
	global_load_lds_dwordx4 v[250:251], off
	v_lshl_add_u64 v[250:251], v[154:155], 0, s[24:25]
	s_add_i32 m0, s79, 0xa000
	s_mov_b64 s[24:25], 0x60080
	global_load_lds_dwordx4 v[250:251], off
	v_lshl_add_u64 v[250:251], v[154:155], 0, s[50:51]
	s_add_i32 m0, s79, 0xc000
	v_lshl_add_u64 v[154:155], v[154:155], 0, s[24:25]
	global_load_lds_dwordx4 v[250:251], off
	s_add_i32 m0, s79, 0xe000
	s_nop 0
	global_load_lds_dwordx4 v[154:155], off
	s_waitcnt lgkmcnt(0)
	s_barrier
	v_mfma_f32_16x16x32_bf16 v[128:131], v[134:137], v[218:221], 0
	v_mfma_f32_16x16x32_bf16 v[124:127], v[142:145], v[218:221], 0
	v_mfma_f32_16x16x32_bf16 v[112:115], v[134:137], v[222:225], 0
	v_mfma_f32_16x16x32_bf16 v[108:111], v[142:145], v[222:225], 0
	v_mfma_f32_16x16x32_bf16 v[96:99], v[134:137], v[234:237], 0
	v_mfma_f32_16x16x32_bf16 v[92:95], v[142:145], v[234:237], 0
	v_mfma_f32_16x16x32_bf16 v[80:83], v[134:137], v[238:241], 0
	v_mfma_f32_16x16x32_bf16 v[76:79], v[142:145], v[238:241], 0
	v_mfma_f32_16x16x32_bf16 v[128:131], v[138:141], v[226:229], v[128:131]
	v_mfma_f32_16x16x32_bf16 v[124:127], v[146:149], v[226:229], v[124:127]
	v_mfma_f32_16x16x32_bf16 v[112:115], v[138:141], v[230:233], v[112:115]
	v_mfma_f32_16x16x32_bf16 v[108:111], v[146:149], v[230:233], v[108:111]
	v_mfma_f32_16x16x32_bf16 v[96:99], v[138:141], v[242:245], v[96:99]
	v_mfma_f32_16x16x32_bf16 v[92:95], v[146:149], v[242:245], v[92:95]
	v_mfma_f32_16x16x32_bf16 v[80:83], v[138:141], v[246:249], v[80:83]
	v_mfma_f32_16x16x32_bf16 v[76:79], v[146:149], v[246:249], v[76:79]
	v_mfma_f32_16x16x32_bf16 v[120:123], v[150:153], v[218:221], 0
	v_mfma_f32_16x16x32_bf16 v[116:119], v[178:181], v[218:221], 0
	v_mfma_f32_16x16x32_bf16 v[104:107], v[150:153], v[222:225], 0
	v_mfma_f32_16x16x32_bf16 v[100:103], v[178:181], v[222:225], 0
	v_mfma_f32_16x16x32_bf16 v[88:91], v[150:153], v[234:237], 0
	v_mfma_f32_16x16x32_bf16 v[84:87], v[178:181], v[234:237], 0
	v_mfma_f32_16x16x32_bf16 v[72:75], v[150:153], v[238:241], 0
	v_mfma_f32_16x16x32_bf16 v[68:71], v[178:181], v[238:241], 0
	v_mfma_f32_16x16x32_bf16 v[120:123], v[174:177], v[226:229], v[120:123]
	v_mfma_f32_16x16x32_bf16 v[116:119], v[182:185], v[226:229], v[116:119]
	v_mfma_f32_16x16x32_bf16 v[104:107], v[174:177], v[230:233], v[104:107]
	v_mfma_f32_16x16x32_bf16 v[100:103], v[182:185], v[230:233], v[100:103]
	v_mfma_f32_16x16x32_bf16 v[88:91], v[174:177], v[242:245], v[88:91]
	v_mfma_f32_16x16x32_bf16 v[84:87], v[182:185], v[242:245], v[84:87]
	v_mfma_f32_16x16x32_bf16 v[72:75], v[174:177], v[246:249], v[72:75]
	v_mfma_f32_16x16x32_bf16 v[68:71], v[182:185], v[246:249], v[68:71]
	s_barrier
	s_add_i32 s24, s1, s77
	v_lshl_add_u64 v[154:155], s[86:87], 0, v[158:159]
	s_mov_b32 m0, s24
	ds_read_b128 v[218:221], v207 offset:16384
	ds_read_b128 v[222:225], v207 offset:18432
	ds_read_b128 v[226:229], v208 offset:16384
	ds_read_b128 v[230:233], v208 offset:18432
	ds_read_b128 v[234:237], v207 offset:20480
	ds_read_b128 v[238:241], v207 offset:22528
	ds_read_b128 v[242:245], v208 offset:20480
	ds_read_b128 v[246:249], v208 offset:22528
	global_load_lds_dwordx4 v[154:155], off
	v_lshl_add_u64 v[250:251], v[154:155], 0, s[14:15]
	s_add_i32 m0, s24, 0x2000
	s_add_i32 s24, s12, s77
	global_load_lds_dwordx4 v[250:251], off
	v_lshl_add_u64 v[250:251], v[154:155], 0, s[16:17]
	s_mov_b32 m0, s24
	s_nop 0
	global_load_lds_dwordx4 v[250:251], off
	v_lshl_add_u64 v[250:251], v[154:155], 0, s[18:19]
	s_add_i32 m0, s24, 0x2000
	s_nop 0
	global_load_lds_dwordx4 v[250:251], off
	s_waitcnt vmcnt(4)
	s_waitcnt lgkmcnt(0)
	s_barrier
	v_mfma_f32_16x16x32_bf16 v[64:67], v[134:137], v[218:221], 0
	v_mfma_f32_16x16x32_bf16 v[60:63], v[142:145], v[218:221], 0
	v_mfma_f32_16x16x32_bf16 v[48:51], v[134:137], v[222:225], 0
	v_mfma_f32_16x16x32_bf16 v[44:47], v[142:145], v[222:225], 0
	v_mfma_f32_16x16x32_bf16 v[32:35], v[134:137], v[234:237], 0
	v_mfma_f32_16x16x32_bf16 v[28:31], v[142:145], v[234:237], 0
	v_mfma_f32_16x16x32_bf16 v[16:19], v[134:137], v[238:241], 0
	v_mfma_f32_16x16x32_bf16 v[12:15], v[142:145], v[238:241], 0
	v_mfma_f32_16x16x32_bf16 v[64:67], v[138:141], v[226:229], v[64:67]
	v_mfma_f32_16x16x32_bf16 v[60:63], v[146:149], v[226:229], v[60:63]
	v_mfma_f32_16x16x32_bf16 v[48:51], v[138:141], v[230:233], v[48:51]
	v_mfma_f32_16x16x32_bf16 v[44:47], v[146:149], v[230:233], v[44:47]
	v_mfma_f32_16x16x32_bf16 v[32:35], v[138:141], v[242:245], v[32:35]
	v_mfma_f32_16x16x32_bf16 v[28:31], v[146:149], v[242:245], v[28:31]
	v_mfma_f32_16x16x32_bf16 v[16:19], v[138:141], v[246:249], v[16:19]
	v_mfma_f32_16x16x32_bf16 v[12:15], v[146:149], v[246:249], v[12:15]
	v_mfma_f32_16x16x32_bf16 v[56:59], v[150:153], v[218:221], 0
	v_mfma_f32_16x16x32_bf16 v[52:55], v[178:181], v[218:221], 0
	v_mfma_f32_16x16x32_bf16 v[40:43], v[150:153], v[222:225], 0
	v_mfma_f32_16x16x32_bf16 v[36:39], v[178:181], v[222:225], 0
	v_mfma_f32_16x16x32_bf16 v[24:27], v[150:153], v[234:237], 0
	v_mfma_f32_16x16x32_bf16 v[20:23], v[178:181], v[234:237], 0
	v_mfma_f32_16x16x32_bf16 v[8:11], v[150:153], v[238:241], 0
	v_mfma_f32_16x16x32_bf16 v[4:7], v[178:181], v[238:241], 0
	v_mfma_f32_16x16x32_bf16 v[56:59], v[174:177], v[226:229], v[56:59]
	v_mfma_f32_16x16x32_bf16 v[52:55], v[182:185], v[226:229], v[52:55]
	v_mfma_f32_16x16x32_bf16 v[40:43], v[174:177], v[230:233], v[40:43]
	v_mfma_f32_16x16x32_bf16 v[36:39], v[182:185], v[230:233], v[36:39]
	v_mfma_f32_16x16x32_bf16 v[24:27], v[174:177], v[242:245], v[24:27]
	v_mfma_f32_16x16x32_bf16 v[20:23], v[182:185], v[242:245], v[20:23]
	v_mfma_f32_16x16x32_bf16 v[8:11], v[174:177], v[246:249], v[8:11]
	v_mfma_f32_16x16x32_bf16 v[4:7], v[182:185], v[246:249], v[4:7]
	s_barrier
	ds_read_b128 v[134:137], v213
	ds_read_b128 v[138:141], v214
	ds_read_b128 v[142:145], v209
	ds_read_b128 v[146:149], v210
	ds_read_b128 v[150:153], v215
	ds_read_b128 v[174:177], v216
	ds_read_b128 v[178:181], v211
	ds_read_b128 v[182:185], v212
	s_mov_b32 m0, s79
	v_lshl_add_u64 v[250:251], s[82:83], 0, v[0:1]
	ds_read_b128 v[218:221], v207 offset:32768
	ds_read_b128 v[222:225], v207 offset:34816
	ds_read_b128 v[226:229], v208 offset:32768
	ds_read_b128 v[230:233], v208 offset:34816
	ds_read_b128 v[234:237], v207 offset:36864
	ds_read_b128 v[238:241], v207 offset:38912
	ds_read_b128 v[242:245], v208 offset:36864
	ds_read_b128 v[246:249], v208 offset:38912
	global_load_lds_dwordx4 v[250:251], off
	v_lshl_add_u64 v[252:253], v[250:251], 0, s[20:21]
	s_mov_b32 m0, s81
	s_nop 0
	global_load_lds_dwordx4 v[252:253], off
	v_lshl_add_u64 v[252:253], v[250:251], 0, s[14:15]
	s_mov_b32 m0, s97
	v_lshl_add_u64 v[250:251], v[250:251], 0, s[22:23]
	global_load_lds_dwordx4 v[252:253], off
	s_mov_b32 m0, s64
	s_nop 0
	global_load_lds_dwordx4 v[250:251], off
	s_waitcnt vmcnt(8)
	s_waitcnt lgkmcnt(0)
	s_barrier
	v_mfma_f32_16x16x32_bf16 v[128:131], v[134:137], v[218:221], v[128:131]
	v_mfma_f32_16x16x32_bf16 v[124:127], v[142:145], v[218:221], v[124:127]
	v_mfma_f32_16x16x32_bf16 v[112:115], v[134:137], v[222:225], v[112:115]
	v_mfma_f32_16x16x32_bf16 v[108:111], v[142:145], v[222:225], v[108:111]
	v_mfma_f32_16x16x32_bf16 v[96:99], v[134:137], v[234:237], v[96:99]
	v_mfma_f32_16x16x32_bf16 v[92:95], v[142:145], v[234:237], v[92:95]
	v_mfma_f32_16x16x32_bf16 v[80:83], v[134:137], v[238:241], v[80:83]
	v_mfma_f32_16x16x32_bf16 v[76:79], v[142:145], v[238:241], v[76:79]
	v_mfma_f32_16x16x32_bf16 v[128:131], v[138:141], v[226:229], v[128:131]
	v_mfma_f32_16x16x32_bf16 v[124:127], v[146:149], v[226:229], v[124:127]
	v_mfma_f32_16x16x32_bf16 v[112:115], v[138:141], v[230:233], v[112:115]
	v_mfma_f32_16x16x32_bf16 v[108:111], v[146:149], v[230:233], v[108:111]
	v_mfma_f32_16x16x32_bf16 v[96:99], v[138:141], v[242:245], v[96:99]
	v_mfma_f32_16x16x32_bf16 v[92:95], v[146:149], v[242:245], v[92:95]
	v_mfma_f32_16x16x32_bf16 v[80:83], v[138:141], v[246:249], v[80:83]
	v_mfma_f32_16x16x32_bf16 v[76:79], v[146:149], v[246:249], v[76:79]
	v_mfma_f32_16x16x32_bf16 v[120:123], v[150:153], v[218:221], v[120:123]
	v_mfma_f32_16x16x32_bf16 v[116:119], v[178:181], v[218:221], v[116:119]
	v_mfma_f32_16x16x32_bf16 v[104:107], v[150:153], v[222:225], v[104:107]
	v_mfma_f32_16x16x32_bf16 v[100:103], v[178:181], v[222:225], v[100:103]
	v_mfma_f32_16x16x32_bf16 v[88:91], v[150:153], v[234:237], v[88:91]
	v_mfma_f32_16x16x32_bf16 v[84:87], v[178:181], v[234:237], v[84:87]
	v_mfma_f32_16x16x32_bf16 v[72:75], v[150:153], v[238:241], v[72:75]
	v_mfma_f32_16x16x32_bf16 v[68:71], v[178:181], v[238:241], v[68:71]
	v_mfma_f32_16x16x32_bf16 v[120:123], v[174:177], v[226:229], v[120:123]
	v_mfma_f32_16x16x32_bf16 v[116:119], v[182:185], v[226:229], v[116:119]
	v_mfma_f32_16x16x32_bf16 v[104:107], v[174:177], v[230:233], v[104:107]
	v_mfma_f32_16x16x32_bf16 v[100:103], v[182:185], v[230:233], v[100:103]
	v_mfma_f32_16x16x32_bf16 v[88:91], v[174:177], v[242:245], v[88:91]
	v_mfma_f32_16x16x32_bf16 v[84:87], v[182:185], v[242:245], v[84:87]
	v_mfma_f32_16x16x32_bf16 v[72:75], v[174:177], v[246:249], v[72:75]
	v_mfma_f32_16x16x32_bf16 v[68:71], v[182:185], v[246:249], v[68:71]
	s_barrier
	s_add_i32 s24, s70, s77
	v_lshl_add_u64 v[250:251], v[154:155], 0, s[48:49]
	s_mov_b32 m0, s24
	ds_read_b128 v[218:221], v207 offset:49152
	ds_read_b128 v[222:225], v207 offset:51200
	ds_read_b128 v[226:229], v208 offset:49152
	ds_read_b128 v[230:233], v208 offset:51200
	ds_read_b128 v[234:237], v207 offset:53248
	ds_read_b128 v[238:241], v207 offset:55296
	ds_read_b128 v[242:245], v208 offset:53248
	ds_read_b128 v[246:249], v208 offset:55296
	global_load_lds_dwordx4 v[250:251], off
	v_lshl_add_u64 v[250:251], v[154:155], 0, s[50:51]
	s_add_i32 m0, s24, 0x2000
	s_add_i32 s24, s71, s77
	global_load_lds_dwordx4 v[250:251], off
	v_lshl_add_u64 v[250:251], v[154:155], 0, s[52:53]
	s_mov_b32 m0, s24
	v_lshl_add_u64 v[154:155], v[154:155], 0, s[54:55]
	global_load_lds_dwordx4 v[250:251], off
	s_add_i32 m0, s24, 0x2000
	s_nop 0
	global_load_lds_dwordx4 v[154:155], off
	s_waitcnt vmcnt(4)
	s_waitcnt lgkmcnt(0)
	s_barrier
	v_mfma_f32_16x16x32_bf16 v[64:67], v[134:137], v[218:221], v[64:67]
	v_mfma_f32_16x16x32_bf16 v[60:63], v[142:145], v[218:221], v[60:63]
	v_mfma_f32_16x16x32_bf16 v[48:51], v[134:137], v[222:225], v[48:51]
	v_mfma_f32_16x16x32_bf16 v[44:47], v[142:145], v[222:225], v[44:47]
	v_mfma_f32_16x16x32_bf16 v[32:35], v[134:137], v[234:237], v[32:35]
	v_mfma_f32_16x16x32_bf16 v[28:31], v[142:145], v[234:237], v[28:31]
	v_mfma_f32_16x16x32_bf16 v[16:19], v[134:137], v[238:241], v[16:19]
	v_mfma_f32_16x16x32_bf16 v[12:15], v[142:145], v[238:241], v[12:15]
	v_mfma_f32_16x16x32_bf16 v[64:67], v[138:141], v[226:229], v[64:67]
	v_mfma_f32_16x16x32_bf16 v[60:63], v[146:149], v[226:229], v[60:63]
	v_mfma_f32_16x16x32_bf16 v[48:51], v[138:141], v[230:233], v[48:51]
	v_mfma_f32_16x16x32_bf16 v[44:47], v[146:149], v[230:233], v[44:47]
	v_mfma_f32_16x16x32_bf16 v[32:35], v[138:141], v[242:245], v[32:35]
	v_mfma_f32_16x16x32_bf16 v[28:31], v[146:149], v[242:245], v[28:31]
	v_mfma_f32_16x16x32_bf16 v[16:19], v[138:141], v[246:249], v[16:19]
	v_mfma_f32_16x16x32_bf16 v[12:15], v[146:149], v[246:249], v[12:15]
	v_mfma_f32_16x16x32_bf16 v[56:59], v[150:153], v[218:221], v[56:59]
	v_mfma_f32_16x16x32_bf16 v[52:55], v[178:181], v[218:221], v[52:55]
	v_mfma_f32_16x16x32_bf16 v[40:43], v[150:153], v[222:225], v[40:43]
	v_mfma_f32_16x16x32_bf16 v[36:39], v[178:181], v[222:225], v[36:39]
	v_mfma_f32_16x16x32_bf16 v[24:27], v[150:153], v[234:237], v[24:27]
	v_mfma_f32_16x16x32_bf16 v[20:23], v[178:181], v[234:237], v[20:23]
	v_mfma_f32_16x16x32_bf16 v[8:11], v[150:153], v[238:241], v[8:11]
	v_mfma_f32_16x16x32_bf16 v[4:7], v[178:181], v[238:241], v[4:7]
	v_mfma_f32_16x16x32_bf16 v[56:59], v[174:177], v[226:229], v[56:59]
	v_mfma_f32_16x16x32_bf16 v[52:55], v[182:185], v[226:229], v[52:55]
	v_mfma_f32_16x16x32_bf16 v[40:43], v[174:177], v[230:233], v[40:43]
	v_mfma_f32_16x16x32_bf16 v[36:39], v[182:185], v[230:233], v[36:39]
	v_mfma_f32_16x16x32_bf16 v[24:27], v[174:177], v[242:245], v[24:27]
	v_mfma_f32_16x16x32_bf16 v[20:23], v[182:185], v[242:245], v[20:23]
	v_mfma_f32_16x16x32_bf16 v[8:11], v[174:177], v[246:249], v[8:11]
	v_mfma_f32_16x16x32_bf16 v[4:7], v[182:185], v[246:249], v[4:7]
	s_barrier
	s_add_i32 s94, s94, 2
	s_add_u32 vcc_lo, vcc_lo, 0x100
	s_addc_u32 vcc_hi, vcc_hi, 0
	s_cmp_gt_u32 s94, 13
	.p2align 6

.LBB0_778:
	s_lshl_b32 s35, s91, 18
	s_lshl_b32 s92, s34, 8
	s_add_i32 s35, s35, s92
	v_mov_b32_e32 v6, v5
	v_mov_b32_e32 v7, v5
	s_add_u32 s93, s26, 0x100
	v_mov_b32_e32 v4, v5
	v_mov_b64_e32 v[10:11], v[6:7]
	v_mov_b64_e32 v[14:15], v[6:7]
	v_mov_b64_e32 v[26:27], v[6:7]
	v_mov_b64_e32 v[30:31], v[6:7]
	v_mov_b64_e32 v[42:43], v[6:7]
	v_mov_b64_e32 v[46:47], v[6:7]
	v_mov_b64_e32 v[58:59], v[6:7]
	v_mov_b64_e32 v[62:63], v[6:7]
	v_mov_b64_e32 v[18:19], v[6:7]
	v_mov_b64_e32 v[22:23], v[6:7]
	v_mov_b64_e32 v[34:35], v[6:7]
	v_mov_b64_e32 v[38:39], v[6:7]
	v_mov_b64_e32 v[50:51], v[6:7]
	v_mov_b64_e32 v[54:55], v[6:7]
	v_mov_b64_e32 v[66:67], v[6:7]
	v_mov_b64_e32 v[70:71], v[6:7]
	v_mov_b64_e32 v[74:75], v[6:7]
	v_mov_b64_e32 v[78:79], v[6:7]
	v_mov_b64_e32 v[90:91], v[6:7]
	v_mov_b64_e32 v[94:95], v[6:7]
	v_mov_b64_e32 v[106:107], v[6:7]
	v_mov_b64_e32 v[110:111], v[6:7]
	v_mov_b64_e32 v[122:123], v[6:7]
	v_mov_b64_e32 v[126:127], v[6:7]
	v_mov_b64_e32 v[82:83], v[6:7]
	v_mov_b64_e32 v[86:87], v[6:7]
	v_mov_b64_e32 v[98:99], v[6:7]
	v_mov_b64_e32 v[102:103], v[6:7]
	v_mov_b64_e32 v[114:115], v[6:7]
	v_mov_b64_e32 v[118:119], v[6:7]
	v_mov_b64_e32 v[130:131], v[6:7]
	v_mov_b64_e32 v[134:135], v[6:7]
	v_add_u32_e32 v178, s35, v175
	v_lshl_add_u64 v[170:171], s[28:29], 0, v[152:153]
	s_addc_u32 s94, s27, 0
	s_mov_b32 s95, -2
	s_mov_b64 s[64:65], 0
	v_mov_b64_e32 v[8:9], v[4:5]
	v_mov_b64_e32 v[12:13], v[4:5]
	v_mov_b64_e32 v[24:25], v[4:5]
	v_mov_b64_e32 v[28:29], v[4:5]
	v_mov_b64_e32 v[40:41], v[4:5]
	v_mov_b64_e32 v[44:45], v[4:5]
	v_mov_b64_e32 v[56:57], v[4:5]
	v_mov_b64_e32 v[60:61], v[4:5]
	v_mov_b64_e32 v[16:17], v[4:5]
	v_mov_b64_e32 v[20:21], v[4:5]
	v_mov_b64_e32 v[32:33], v[4:5]
	v_mov_b64_e32 v[36:37], v[4:5]
	v_mov_b64_e32 v[48:49], v[4:5]
	v_mov_b64_e32 v[52:53], v[4:5]
	v_mov_b64_e32 v[64:65], v[4:5]
	v_mov_b64_e32 v[68:69], v[4:5]
	v_mov_b64_e32 v[72:73], v[4:5]
	v_mov_b64_e32 v[76:77], v[4:5]
	v_mov_b64_e32 v[88:89], v[4:5]
	v_mov_b64_e32 v[92:93], v[4:5]
	v_mov_b64_e32 v[104:105], v[4:5]
	v_mov_b64_e32 v[108:109], v[4:5]
	v_mov_b64_e32 v[120:121], v[4:5]
	v_mov_b64_e32 v[124:125], v[4:5]
	v_mov_b64_e32 v[80:81], v[4:5]
	v_mov_b64_e32 v[84:85], v[4:5]
	v_mov_b64_e32 v[96:97], v[4:5]
	v_mov_b64_e32 v[100:101], v[4:5]
	v_mov_b64_e32 v[112:113], v[4:5]
	v_mov_b64_e32 v[116:117], v[4:5]
	v_mov_b64_e32 v[128:129], v[4:5]
	v_mov_b64_e32 v[132:133], v[4:5]
	s_branch .LBB0_780
	.p2align 6

.LBB0_972:
	s_add_u32 s65, s26, 0x100
	s_addc_u32 s85, s27, 0
	s_ashr_i32 s63, s62, 31
	s_lshl_b64 s[66:67], s[62:63], 19
	s_add_u32 s68, s40, s66
	s_addc_u32 s69, s41, s67
	s_and_b64 s[66:67], s[14:15], exec
	s_cselect_b32 s54, s69, s29
	s_cselect_b32 s63, s68, s28
	s_ashr_i32 s61, s60, 31
	s_lshl_b64 s[66:67], s[60:61], 19
	v_readlane_b32 s70, v254, 5
	v_readlane_b32 s71, v254, 6
	s_add_u32 s66, s70, s66
	s_addc_u32 s67, s71, s67
	s_and_b64 s[70:71], s[14:15], exec
	s_cselect_b32 s61, s67, s27
	s_cselect_b32 s88, s66, s26
	v_lshl_add_u64 v[134:135], s[28:29], 0, v[142:143]
	s_mov_b32 s89, -2
	s_mov_b64 s[26:27], 0
	.p2align 6

.LBB0_1134:
	s_ashr_i32 s57, s56, 31
	s_lshl_b64 s[60:61], s[56:57], 19
	s_add_u32 s60, s42, s60
	s_addc_u32 s61, s43, s61
	s_and_b64 s[62:63], s[10:11], exec
	s_cselect_b32 s57, s61, s27
	s_cselect_b32 s79, s60, s26
	s_ashr_i32 s59, s58, 31
	s_lshl_b64 s[62:63], s[58:59], 19
	v_readlane_b32 s70, v254, 7
	v_readlane_b32 s71, v254, 8
	s_add_u32 s62, s70, s62
	s_addc_u32 s63, s71, s63
	s_and_b64 s[70:71], s[10:11], exec
	s_cselect_b32 s59, s63, s69
	s_cselect_b32 s80, s62, s68
	s_add_u32 s81, s68, 0x100
	v_lshl_add_u64 v[138:139], s[26:27], 0, v[132:133]
	s_addc_u32 s82, s69, 0
	s_mov_b32 s83, -2
	s_mov_b64 s[68:69], 0
	ds_read_b128 v[168:171], v145
	ds_read_b128 v[174:177], v146
	ds_read_b128 v[178:181], v147
	ds_read_b128 v[182:185], v148
	ds_read_b128 v[194:197], v149
	ds_read_b128 v[198:201], v150
	ds_read_b128 v[202:205], v151
	ds_read_b128 v[206:209], v152
	s_add_u32 s70, s26, s68
	s_addc_u32 s71, s27, s69
	s_add_u32 s70, s70, 0x100
	s_addc_u32 s71, s71, 0
	s_add_u32 s84, s81, s68
	s_addc_u32 s85, s82, s69
	s_cmpk_eq_i32 s68, 0x700
	s_cselect_b32 s85, s59, s85
	s_cselect_b32 s84, s80, s84
	s_cselect_b32 s71, s57, s71
	s_cselect_b32 s70, s79, s70
	v_lshl_add_u64 v[140:141], v[138:139], 0, s[68:69]
	v_lshl_add_u64 v[242:243], v[140:141], 0, s[22:23]
	s_add_i32 m0, s34, 0x8000
	s_mov_b64 s[86:87], 0x20080
	ds_read_b128 v[210:213], v153
	ds_read_b128 v[214:217], v153 offset:2048
	ds_read_b128 v[218:221], v154
	ds_read_b128 v[222:225], v154 offset:2048
	ds_read_b128 v[226:229], v153 offset:4096
	ds_read_b128 v[230:233], v153 offset:6144
	ds_read_b128 v[234:237], v154 offset:4096
	ds_read_b128 v[238:241], v154 offset:6144
	global_load_lds_dwordx4 v[242:243], off
	v_lshl_add_u64 v[242:243], v[140:141], 0, s[86:87]
	s_add_i32 m0, s34, 0xa000
	s_mov_b64 s[86:87], 0x60080
	global_load_lds_dwordx4 v[242:243], off
	v_lshl_add_u64 v[242:243], v[140:141], 0, s[24:25]
	s_add_i32 m0, s34, 0xc000
	v_lshl_add_u64 v[140:141], v[140:141], 0, s[86:87]
	global_load_lds_dwordx4 v[242:243], off
	s_add_i32 m0, s34, 0xe000
	s_nop 0
	global_load_lds_dwordx4 v[140:141], off
	s_waitcnt lgkmcnt(0)
	s_barrier
	v_mfma_f32_16x16x32_bf16 v[128:131], v[168:171], v[210:213], 0
	v_mfma_f32_16x16x32_bf16 v[124:127], v[178:181], v[210:213], 0
	v_mfma_f32_16x16x32_bf16 v[112:115], v[168:171], v[214:217], 0
	v_mfma_f32_16x16x32_bf16 v[108:111], v[178:181], v[214:217], 0
	v_mfma_f32_16x16x32_bf16 v[96:99], v[168:171], v[226:229], 0
	v_mfma_f32_16x16x32_bf16 v[92:95], v[178:181], v[226:229], 0
	v_mfma_f32_16x16x32_bf16 v[80:83], v[168:171], v[230:233], 0
	v_mfma_f32_16x16x32_bf16 v[76:79], v[178:181], v[230:233], 0
	v_mfma_f32_16x16x32_bf16 v[128:131], v[174:177], v[218:221], v[128:131]
	v_mfma_f32_16x16x32_bf16 v[124:127], v[182:185], v[218:221], v[124:127]
	v_mfma_f32_16x16x32_bf16 v[112:115], v[174:177], v[222:225], v[112:115]
	v_mfma_f32_16x16x32_bf16 v[108:111], v[182:185], v[222:225], v[108:111]
	v_mfma_f32_16x16x32_bf16 v[96:99], v[174:177], v[234:237], v[96:99]
	v_mfma_f32_16x16x32_bf16 v[92:95], v[182:185], v[234:237], v[92:95]
	v_mfma_f32_16x16x32_bf16 v[80:83], v[174:177], v[238:241], v[80:83]
	v_mfma_f32_16x16x32_bf16 v[76:79], v[182:185], v[238:241], v[76:79]
	v_mfma_f32_16x16x32_bf16 v[120:123], v[194:197], v[210:213], 0
	v_mfma_f32_16x16x32_bf16 v[116:119], v[202:205], v[210:213], 0
	v_mfma_f32_16x16x32_bf16 v[104:107], v[194:197], v[214:217], 0
	v_mfma_f32_16x16x32_bf16 v[100:103], v[202:205], v[214:217], 0
	v_mfma_f32_16x16x32_bf16 v[88:91], v[194:197], v[226:229], 0
	v_mfma_f32_16x16x32_bf16 v[84:87], v[202:205], v[226:229], 0
	v_mfma_f32_16x16x32_bf16 v[72:75], v[194:197], v[230:233], 0
	v_mfma_f32_16x16x32_bf16 v[68:71], v[202:205], v[230:233], 0
	v_mfma_f32_16x16x32_bf16 v[120:123], v[198:201], v[218:221], v[120:123]
	v_mfma_f32_16x16x32_bf16 v[116:119], v[206:209], v[218:221], v[116:119]
	v_mfma_f32_16x16x32_bf16 v[104:107], v[198:201], v[222:225], v[104:107]
	v_mfma_f32_16x16x32_bf16 v[100:103], v[206:209], v[222:225], v[100:103]
	v_mfma_f32_16x16x32_bf16 v[88:91], v[198:201], v[234:237], v[88:91]
	v_mfma_f32_16x16x32_bf16 v[84:87], v[206:209], v[234:237], v[84:87]
	v_mfma_f32_16x16x32_bf16 v[72:75], v[198:201], v[238:241], v[72:75]
	v_mfma_f32_16x16x32_bf16 v[68:71], v[206:209], v[238:241], v[68:71]
	s_barrier
	v_lshl_add_u64 v[140:141], s[84:85], 0, v[158:159]
	s_add_i32 s84, s67, s3
	s_mov_b32 m0, s84
	ds_read_b128 v[210:213], v153 offset:16384
	ds_read_b128 v[214:217], v153 offset:18432
	ds_read_b128 v[218:221], v154 offset:16384
	ds_read_b128 v[222:225], v154 offset:18432
	ds_read_b128 v[226:229], v153 offset:20480
	ds_read_b128 v[230:233], v153 offset:22528
	ds_read_b128 v[234:237], v154 offset:20480
	ds_read_b128 v[238:241], v154 offset:22528
	global_load_lds_dwordx4 v[140:141], off
	v_lshl_add_u64 v[242:243], v[140:141], 0, s[0:1]
	s_add_i32 m0, s84, 0x2000
	s_add_i32 s84, s72, s3
	global_load_lds_dwordx4 v[242:243], off
	v_lshl_add_u64 v[242:243], v[140:141], 0, s[12:13]
	s_mov_b32 m0, s84
	s_nop 0
	global_load_lds_dwordx4 v[242:243], off
	v_lshl_add_u64 v[242:243], v[140:141], 0, s[14:15]
	s_add_i32 m0, s84, 0x2000
	s_nop 0
	global_load_lds_dwordx4 v[242:243], off
	s_waitcnt vmcnt(4)
	s_waitcnt lgkmcnt(0)
	s_barrier
	v_mfma_f32_16x16x32_bf16 v[64:67], v[168:171], v[210:213], 0
	v_mfma_f32_16x16x32_bf16 v[60:63], v[178:181], v[210:213], 0
	v_mfma_f32_16x16x32_bf16 v[48:51], v[168:171], v[214:217], 0
	v_mfma_f32_16x16x32_bf16 v[44:47], v[178:181], v[214:217], 0
	v_mfma_f32_16x16x32_bf16 v[32:35], v[168:171], v[226:229], 0
	v_mfma_f32_16x16x32_bf16 v[28:31], v[178:181], v[226:229], 0
	v_mfma_f32_16x16x32_bf16 v[16:19], v[168:171], v[230:233], 0
	v_mfma_f32_16x16x32_bf16 v[12:15], v[178:181], v[230:233], 0
	v_mfma_f32_16x16x32_bf16 v[64:67], v[174:177], v[218:221], v[64:67]
	v_mfma_f32_16x16x32_bf16 v[60:63], v[182:185], v[218:221], v[60:63]
	v_mfma_f32_16x16x32_bf16 v[48:51], v[174:177], v[222:225], v[48:51]
	v_mfma_f32_16x16x32_bf16 v[44:47], v[182:185], v[222:225], v[44:47]
	v_mfma_f32_16x16x32_bf16 v[32:35], v[174:177], v[234:237], v[32:35]
	v_mfma_f32_16x16x32_bf16 v[28:31], v[182:185], v[234:237], v[28:31]
	v_mfma_f32_16x16x32_bf16 v[16:19], v[174:177], v[238:241], v[16:19]
	v_mfma_f32_16x16x32_bf16 v[12:15], v[182:185], v[238:241], v[12:15]
	v_mfma_f32_16x16x32_bf16 v[56:59], v[194:197], v[210:213], 0
	v_mfma_f32_16x16x32_bf16 v[52:55], v[202:205], v[210:213], 0
	v_mfma_f32_16x16x32_bf16 v[40:43], v[194:197], v[214:217], 0
	v_mfma_f32_16x16x32_bf16 v[36:39], v[202:205], v[214:217], 0
	v_mfma_f32_16x16x32_bf16 v[24:27], v[194:197], v[226:229], 0
	v_mfma_f32_16x16x32_bf16 v[20:23], v[202:205], v[226:229], 0
	v_mfma_f32_16x16x32_bf16 v[8:11], v[194:197], v[230:233], 0
	v_mfma_f32_16x16x32_bf16 v[4:7], v[202:205], v[230:233], 0
	v_mfma_f32_16x16x32_bf16 v[56:59], v[198:201], v[218:221], v[56:59]
	v_mfma_f32_16x16x32_bf16 v[52:55], v[206:209], v[218:221], v[52:55]
	v_mfma_f32_16x16x32_bf16 v[40:43], v[198:201], v[222:225], v[40:43]
	v_mfma_f32_16x16x32_bf16 v[36:39], v[206:209], v[222:225], v[36:39]
	v_mfma_f32_16x16x32_bf16 v[24:27], v[198:201], v[234:237], v[24:27]
	v_mfma_f32_16x16x32_bf16 v[20:23], v[206:209], v[234:237], v[20:23]
	v_mfma_f32_16x16x32_bf16 v[8:11], v[198:201], v[238:241], v[8:11]
	v_mfma_f32_16x16x32_bf16 v[4:7], v[206:209], v[238:241], v[4:7]
	s_barrier
	ds_read_b128 v[168:171], v163
	ds_read_b128 v[174:177], v164
	ds_read_b128 v[178:181], v155
	ds_read_b128 v[182:185], v160
	ds_read_b128 v[194:197], v165
	ds_read_b128 v[198:201], v166
	ds_read_b128 v[202:205], v161
	ds_read_b128 v[206:209], v162
	s_mov_b32 m0, s34
	v_lshl_add_u64 v[242:243], s[70:71], 0, v[0:1]
	ds_read_b128 v[210:213], v153 offset:32768
	ds_read_b128 v[214:217], v153 offset:34816
	ds_read_b128 v[218:221], v154 offset:32768
	ds_read_b128 v[222:225], v154 offset:34816
	ds_read_b128 v[226:229], v153 offset:36864
	ds_read_b128 v[230:233], v153 offset:38912
	ds_read_b128 v[234:237], v154 offset:36864
	ds_read_b128 v[238:241], v154 offset:38912
	global_load_lds_dwordx4 v[242:243], off
	v_lshl_add_u64 v[244:245], v[242:243], 0, s[16:17]
	s_mov_b32 m0, s35
	s_nop 0
	global_load_lds_dwordx4 v[244:245], off
	v_lshl_add_u64 v[244:245], v[242:243], 0, s[0:1]
	s_mov_b32 m0, s38
	v_lshl_add_u64 v[242:243], v[242:243], 0, s[18:19]
	global_load_lds_dwordx4 v[244:245], off
	s_mov_b32 m0, s39
	s_nop 0
	global_load_lds_dwordx4 v[242:243], off
	s_waitcnt vmcnt(8)
	s_waitcnt lgkmcnt(0)
	s_barrier
	v_mfma_f32_16x16x32_bf16 v[128:131], v[168:171], v[210:213], v[128:131]
	v_mfma_f32_16x16x32_bf16 v[124:127], v[178:181], v[210:213], v[124:127]
	v_mfma_f32_16x16x32_bf16 v[112:115], v[168:171], v[214:217], v[112:115]
	v_mfma_f32_16x16x32_bf16 v[108:111], v[178:181], v[214:217], v[108:111]
	v_mfma_f32_16x16x32_bf16 v[96:99], v[168:171], v[226:229], v[96:99]
	v_mfma_f32_16x16x32_bf16 v[92:95], v[178:181], v[226:229], v[92:95]
	v_mfma_f32_16x16x32_bf16 v[80:83], v[168:171], v[230:233], v[80:83]
	v_mfma_f32_16x16x32_bf16 v[76:79], v[178:181], v[230:233], v[76:79]
	v_mfma_f32_16x16x32_bf16 v[128:131], v[174:177], v[218:221], v[128:131]
	v_mfma_f32_16x16x32_bf16 v[124:127], v[182:185], v[218:221], v[124:127]
	v_mfma_f32_16x16x32_bf16 v[112:115], v[174:177], v[222:225], v[112:115]
	v_mfma_f32_16x16x32_bf16 v[108:111], v[182:185], v[222:225], v[108:111]
	v_mfma_f32_16x16x32_bf16 v[96:99], v[174:177], v[234:237], v[96:99]
	v_mfma_f32_16x16x32_bf16 v[92:95], v[182:185], v[234:237], v[92:95]
	v_mfma_f32_16x16x32_bf16 v[80:83], v[174:177], v[238:241], v[80:83]
	v_mfma_f32_16x16x32_bf16 v[76:79], v[182:185], v[238:241], v[76:79]
	v_mfma_f32_16x16x32_bf16 v[120:123], v[194:197], v[210:213], v[120:123]
	v_mfma_f32_16x16x32_bf16 v[116:119], v[202:205], v[210:213], v[116:119]
	v_mfma_f32_16x16x32_bf16 v[104:107], v[194:197], v[214:217], v[104:107]
	v_mfma_f32_16x16x32_bf16 v[100:103], v[202:205], v[214:217], v[100:103]
	v_mfma_f32_16x16x32_bf16 v[88:91], v[194:197], v[226:229], v[88:91]
	v_mfma_f32_16x16x32_bf16 v[84:87], v[202:205], v[226:229], v[84:87]
	v_mfma_f32_16x16x32_bf16 v[72:75], v[194:197], v[230:233], v[72:75]
	v_mfma_f32_16x16x32_bf16 v[68:71], v[202:205], v[230:233], v[68:71]
	v_mfma_f32_16x16x32_bf16 v[120:123], v[198:201], v[218:221], v[120:123]
	v_mfma_f32_16x16x32_bf16 v[116:119], v[206:209], v[218:221], v[116:119]
	v_mfma_f32_16x16x32_bf16 v[104:107], v[198:201], v[222:225], v[104:107]
	v_mfma_f32_16x16x32_bf16 v[100:103], v[206:209], v[222:225], v[100:103]
	v_mfma_f32_16x16x32_bf16 v[88:91], v[198:201], v[234:237], v[88:91]
	v_mfma_f32_16x16x32_bf16 v[84:87], v[206:209], v[234:237], v[84:87]
	v_mfma_f32_16x16x32_bf16 v[72:75], v[198:201], v[238:241], v[72:75]
	v_mfma_f32_16x16x32_bf16 v[68:71], v[206:209], v[238:241], v[68:71]
	s_barrier
	s_add_i32 s70, s73, s3
	v_lshl_add_u64 v[242:243], v[140:141], 0, s[22:23]
	s_mov_b32 m0, s70
	ds_read_b128 v[210:213], v153 offset:49152
	ds_read_b128 v[214:217], v153 offset:51200
	ds_read_b128 v[218:221], v154 offset:49152
	ds_read_b128 v[222:225], v154 offset:51200
	ds_read_b128 v[226:229], v153 offset:53248
	ds_read_b128 v[230:233], v153 offset:55296
	ds_read_b128 v[234:237], v154 offset:53248
	ds_read_b128 v[238:241], v154 offset:55296
	global_load_lds_dwordx4 v[242:243], off
	v_lshl_add_u64 v[242:243], v[140:141], 0, s[24:25]
	s_add_i32 m0, s70, 0x2000
	s_add_i32 s70, s77, s3
	global_load_lds_dwordx4 v[242:243], off
	v_lshl_add_u64 v[242:243], v[140:141], 0, s[28:29]
	s_mov_b32 m0, s70
	v_lshl_add_u64 v[140:141], v[140:141], 0, s[36:37]
	global_load_lds_dwordx4 v[242:243], off
	s_add_i32 m0, s70, 0x2000
	s_nop 0
	global_load_lds_dwordx4 v[140:141], off
	s_waitcnt vmcnt(4)
	s_waitcnt lgkmcnt(0)
	s_barrier
	v_mfma_f32_16x16x32_bf16 v[64:67], v[168:171], v[210:213], v[64:67]
	v_mfma_f32_16x16x32_bf16 v[60:63], v[178:181], v[210:213], v[60:63]
	v_mfma_f32_16x16x32_bf16 v[48:51], v[168:171], v[214:217], v[48:51]
	v_mfma_f32_16x16x32_bf16 v[44:47], v[178:181], v[214:217], v[44:47]
	v_mfma_f32_16x16x32_bf16 v[32:35], v[168:171], v[226:229], v[32:35]
	v_mfma_f32_16x16x32_bf16 v[28:31], v[178:181], v[226:229], v[28:31]
	v_mfma_f32_16x16x32_bf16 v[16:19], v[168:171], v[230:233], v[16:19]
	v_mfma_f32_16x16x32_bf16 v[12:15], v[178:181], v[230:233], v[12:15]
	v_mfma_f32_16x16x32_bf16 v[64:67], v[174:177], v[218:221], v[64:67]
	v_mfma_f32_16x16x32_bf16 v[60:63], v[182:185], v[218:221], v[60:63]
	v_mfma_f32_16x16x32_bf16 v[48:51], v[174:177], v[222:225], v[48:51]
	v_mfma_f32_16x16x32_bf16 v[44:47], v[182:185], v[222:225], v[44:47]
	v_mfma_f32_16x16x32_bf16 v[32:35], v[174:177], v[234:237], v[32:35]
	v_mfma_f32_16x16x32_bf16 v[28:31], v[182:185], v[234:237], v[28:31]
	v_mfma_f32_16x16x32_bf16 v[16:19], v[174:177], v[238:241], v[16:19]
	v_mfma_f32_16x16x32_bf16 v[12:15], v[182:185], v[238:241], v[12:15]
	v_mfma_f32_16x16x32_bf16 v[56:59], v[194:197], v[210:213], v[56:59]
	v_mfma_f32_16x16x32_bf16 v[52:55], v[202:205], v[210:213], v[52:55]
	v_mfma_f32_16x16x32_bf16 v[40:43], v[194:197], v[214:217], v[40:43]
	v_mfma_f32_16x16x32_bf16 v[36:39], v[202:205], v[214:217], v[36:39]
	v_mfma_f32_16x16x32_bf16 v[24:27], v[194:197], v[226:229], v[24:27]
	v_mfma_f32_16x16x32_bf16 v[20:23], v[202:205], v[226:229], v[20:23]
	v_mfma_f32_16x16x32_bf16 v[8:11], v[194:197], v[230:233], v[8:11]
	v_mfma_f32_16x16x32_bf16 v[4:7], v[202:205], v[230:233], v[4:7]
	v_mfma_f32_16x16x32_bf16 v[56:59], v[198:201], v[218:221], v[56:59]
	v_mfma_f32_16x16x32_bf16 v[52:55], v[206:209], v[218:221], v[52:55]
	v_mfma_f32_16x16x32_bf16 v[40:43], v[198:201], v[222:225], v[40:43]
	v_mfma_f32_16x16x32_bf16 v[36:39], v[206:209], v[222:225], v[36:39]
	v_mfma_f32_16x16x32_bf16 v[24:27], v[198:201], v[234:237], v[24:27]
	v_mfma_f32_16x16x32_bf16 v[20:23], v[206:209], v[234:237], v[20:23]
	v_mfma_f32_16x16x32_bf16 v[8:11], v[198:201], v[238:241], v[8:11]
	v_mfma_f32_16x16x32_bf16 v[4:7], v[206:209], v[238:241], v[4:7]
	s_barrier
	s_add_i32 s83, s83, 2
	s_add_u32 s68, s68, 0x100
	s_addc_u32 s69, s69, 0
	s_cmp_gt_u32 s83, 13
	.p2align 6

.LBB0_1370:
	s_add_u32 s53, s56, 0x100
	s_addc_u32 s72, s57, 0
	s_ashr_i32 s51, s50, 31
	s_lshl_b64 s[26:27], s[50:51], 21
	s_add_u32 s54, s30, s26
	s_addc_u32 s55, s31, s27
	s_and_b64 s[26:27], s[6:7], exec
	s_cselect_b32 s51, s55, s19
	s_cselect_b32 s73, s54, s18
	s_ashr_i32 s49, s48, 31
	s_lshl_b64 s[26:27], s[48:49], 21
	v_readlane_b32 s58, v254, 9
	v_readlane_b32 s59, v254, 10
	s_add_u32 s26, s58, s26
	s_addc_u32 s27, s59, s27
	s_and_b64 s[58:59], s[6:7], exec
	s_cselect_b32 s49, s27, s57
	s_cselect_b32 s76, s26, s56
	v_lshl_add_u64 v[140:141], s[18:19], 0, v[134:135]
	s_mov_b32 s77, -2
	s_mov_b64 s[56:57], 0
	.p2align 6
